# speedup vs baseline: 1.0169x; 1.0169x over previous
; #define LAS __attribute__((address_space(3)))
; #define MFMA32(a, b, c) __builtin_amdgcn_mfma_f32_32x32x16_bf16((a), (b), (c), 0, 0, 0)
; DI void attn_unit(const Params& P, LAS unsigned char* lds, int b, int h, int qb, bool dry) {
;     ...
;     auto qk_softmax = [&](int kt, int kslot, bool domask) {
;         const LAS unsigned char* kb_ = Ks + kslot * KS_BYTES + r * KS_STRIDE + 16 * hh;
;         f32x16 s0, s1;
;         __builtin_amdgcn_s_setprio(1);
;         { const f32x16 z16 = {0.f, 0.f, 0.f, 0.f, 0.f, 0.f, 0.f, 0.f, 0.f, 0.f, 0.f, 0.f, 0.f, 0.f, 0.f, 0.f};
;           const bf16x8 a0 = *(const LAS bf16x8*)(kb_), a1 = *(const LAS bf16x8*)(kb_ + 32 * KS_STRIDE);
;           s0 = MFMA32(a0, qf[0], z16); s1 = MFMA32(a1, qf[0], z16); }
; #pragma unroll
;         for (int s = 1; s < 12; ++s) {
;             const bf16x8 a0 = *(const LAS bf16x8*)(kb_ + 32 * s), a1 = *(const LAS bf16x8*)(kb_ + 32 * KS_STRIDE + 32 * s);
;             s0 = MFMA32(a0, qf[s], s0); s1 = MFMA32(a1, qf[s], s1);
;         }
;         __builtin_amdgcn_s_setprio(0);
.LBB0_35:
	s_add_i32 s80, s62, s20
	s_add_i32 s40, s80, -2
	s_cmp_gt_i32 s40, s26
	v_add_u32_e32 v220, v213, v184
	s_cbranch_scc1 .LBB0_41
	s_add_i32 s40, s63, s20
	s_cmp_lg_u32 s40, 2
	s_setprio 1
	ds_read_b128 v[222:225], v220
	ds_read_b128 v[226:229], v220 offset:12800
	ds_read_b128 v[230:233], v220 offset:32
	ds_read_b128 v[234:237], v220 offset:12832
	s_waitcnt lgkmcnt(3)
	v_mfma_f32_32x32x16_bf16 v[80:95], v[222:225], v[96:99], 0
	ds_read_b128 v[222:225], v220 offset:64
	s_waitcnt lgkmcnt(3)
	v_mfma_f32_32x32x16_bf16 v[64:79], v[226:229], v[96:99], 0
	ds_read_b128 v[226:229], v220 offset:12864
	s_waitcnt lgkmcnt(3)
	v_mfma_f32_32x32x16_bf16 v[80:95], v[230:233], v[100:103], v[80:95]
	ds_read_b128 v[230:233], v220 offset:96
	s_waitcnt lgkmcnt(3)
	v_mfma_f32_32x32x16_bf16 v[64:79], v[234:237], v[100:103], v[64:79]
	ds_read_b128 v[234:237], v220 offset:12896
	s_waitcnt lgkmcnt(3)
	v_mfma_f32_32x32x16_bf16 v[80:95], v[222:225], v[104:107], v[80:95]
	ds_read_b128 v[222:225], v220 offset:128
	s_waitcnt lgkmcnt(3)
	v_mfma_f32_32x32x16_bf16 v[64:79], v[226:229], v[104:107], v[64:79]
	ds_read_b128 v[226:229], v220 offset:12928
	s_waitcnt lgkmcnt(3)
	v_mfma_f32_32x32x16_bf16 v[80:95], v[230:233], v[108:111], v[80:95]
	ds_read_b128 v[230:233], v220 offset:160
	s_waitcnt lgkmcnt(3)
	v_mfma_f32_32x32x16_bf16 v[64:79], v[234:237], v[108:111], v[64:79]
	ds_read_b128 v[234:237], v220 offset:12960
	s_waitcnt lgkmcnt(3)
	v_mfma_f32_32x32x16_bf16 v[80:95], v[222:225], v[112:115], v[80:95]
	ds_read_b128 v[222:225], v220 offset:192
	s_waitcnt lgkmcnt(3)
	v_mfma_f32_32x32x16_bf16 v[64:79], v[226:229], v[112:115], v[64:79]
	ds_read_b128 v[226:229], v220 offset:12992
	s_waitcnt lgkmcnt(3)
	v_mfma_f32_32x32x16_bf16 v[80:95], v[230:233], v[116:119], v[80:95]
	ds_read_b128 v[230:233], v220 offset:224
	s_waitcnt lgkmcnt(3)
	v_mfma_f32_32x32x16_bf16 v[64:79], v[234:237], v[116:119], v[64:79]
	ds_read_b128 v[234:237], v220 offset:13024
	s_waitcnt lgkmcnt(3)
	v_mfma_f32_32x32x16_bf16 v[80:95], v[222:225], v[120:123], v[80:95]
	ds_read_b128 v[222:225], v220 offset:256
	s_waitcnt lgkmcnt(3)
	v_mfma_f32_32x32x16_bf16 v[64:79], v[226:229], v[120:123], v[64:79]
	ds_read_b128 v[226:229], v220 offset:13056
	s_waitcnt lgkmcnt(3)
	v_mfma_f32_32x32x16_bf16 v[80:95], v[230:233], v[124:127], v[80:95]
	ds_read_b128 v[230:233], v220 offset:288
	s_waitcnt lgkmcnt(3)
	v_mfma_f32_32x32x16_bf16 v[64:79], v[234:237], v[124:127], v[64:79]
	ds_read_b128 v[234:237], v220 offset:13088
	s_waitcnt lgkmcnt(3)
	v_mfma_f32_32x32x16_bf16 v[80:95], v[222:225], v[128:131], v[80:95]
	ds_read_b128 v[222:225], v220 offset:320
	s_waitcnt lgkmcnt(3)
	v_mfma_f32_32x32x16_bf16 v[64:79], v[226:229], v[128:131], v[64:79]
	ds_read_b128 v[226:229], v220 offset:13120
	s_waitcnt lgkmcnt(3)
	v_mfma_f32_32x32x16_bf16 v[80:95], v[230:233], v[132:135], v[80:95]
	ds_read_b128 v[230:233], v220 offset:352
	s_waitcnt lgkmcnt(3)
	v_mfma_f32_32x32x16_bf16 v[64:79], v[234:237], v[132:135], v[64:79]
	ds_read_b128 v[234:237], v220 offset:13152
	s_waitcnt lgkmcnt(3)
	v_mfma_f32_32x32x16_bf16 v[80:95], v[222:225], v[136:139], v[80:95]
	s_waitcnt lgkmcnt(2)
	v_mfma_f32_32x32x16_bf16 v[64:79], v[226:229], v[136:139], v[64:79]
	s_waitcnt lgkmcnt(1)
	v_mfma_f32_32x32x16_bf16 v[80:95], v[230:233], v[140:143], v[80:95]
	s_waitcnt lgkmcnt(0)
	v_mfma_f32_32x32x16_bf16 v[64:79], v[234:237], v[140:143], v[64:79]
	s_setprio 0
	s_nop 0
	s_mov_b64 vcc, s[52:53]
	s_cbranch_vccnz .Lattn_hw0_v5
	s_waitcnt vmcnt(0)
	s_branch .Lattn_hw0_go
.Lattn_hw0_v5:
	s_waitcnt vmcnt(5)
; DI void attn_unit(const Params& P, LAS unsigned char* lds, int b, int h, int qb, bool dry) {
;     ...
;         if (domask) {
;             const int qg = q0 + r, kbase = 64 * kt + 4 * hh;
; #pragma unroll
;             for (int i = 0; i < 16; ++i) { const int kk = kbase + (i & 3) + 8 * (i >> 2);
;                 if (kk > qg) s0[i] = -INFINITY;
;                 if (kk + 32 > qg) s1[i] = -INFINITY; }
;         }
.Lattn_hw0_go:
	v_add_u32_e32 v238, 0x10c00, v209
	ds_write_b128 v207, v[144:147] offset:25600
	ds_write_b128 v207, v[148:151] offset:38400
	ds_write_b128 v217, v[152:155] offset:25856
	ds_write2_b64 v238, v[156:157], v[158:159] offset1:1
	v_add_u32_e32 v238, 0x2200, v238
	ds_write2_b64 v238, v[160:161], v[162:163] offset1:1
	s_cbranch_scc1 .LBB0_38
	v_add_u32_e32 v221, 32, v219
	v_cmp_le_i32_e32 vcc, v221, v214
	v_add_u32_e32 v221, 33, v219
	s_nop 6
	v_cndmask_b32_e32 v64, v202, v64, vcc
	v_cmp_lt_i32_e32 vcc, v219, v214
	s_nop 1
	v_cndmask_b32_e32 v81, v202, v81, vcc
	v_cmp_le_i32_e32 vcc, v219, v214
	s_nop 1
	v_cndmask_b32_e32 v80, v202, v80, vcc
	v_cmp_le_i32_e32 vcc, v221, v214
	v_add_u32_e32 v221, 2, v219
	s_nop 0
	v_cndmask_b32_e32 v65, v202, v65, vcc
	v_cmp_le_i32_e32 vcc, v221, v214
	v_add_u32_e32 v221, 34, v219
	s_nop 0
	v_cndmask_b32_e32 v82, v202, v82, vcc
	v_cmp_le_i32_e32 vcc, v221, v214
	v_add_u32_e32 v221, 3, v219
	s_nop 0
	v_cndmask_b32_e32 v66, v202, v66, vcc
	v_cmp_le_i32_e32 vcc, v221, v214
	v_add_u32_e32 v221, 35, v219
	s_nop 0
	v_cndmask_b32_e32 v83, v202, v83, vcc
	v_cmp_le_i32_e32 vcc, v221, v214
	v_add_u32_e32 v221, 8, v219
	s_nop 0
	v_cndmask_b32_e32 v67, v202, v67, vcc
	v_cmp_le_i32_e32 vcc, v221, v214
	v_add_u32_e32 v221, 40, v219
	s_nop 0
	v_cndmask_b32_e32 v84, v202, v84, vcc
	v_cmp_le_i32_e32 vcc, v221, v214
	v_add_u32_e32 v221, 9, v219
	s_nop 0
	v_cndmask_b32_e32 v68, v202, v68, vcc
	v_cmp_le_i32_e32 vcc, v221, v214
	v_add_u32_e32 v221, 41, v219
	s_nop 0
	v_cndmask_b32_e32 v85, v202, v85, vcc
	v_cmp_le_i32_e32 vcc, v221, v214
	v_add_u32_e32 v221, 10, v219
	s_nop 0
	v_cndmask_b32_e32 v69, v202, v69, vcc
	v_cmp_le_i32_e32 vcc, v221, v214
	v_add_u32_e32 v221, 42, v219
	s_nop 0
	v_cndmask_b32_e32 v86, v202, v86, vcc
	v_cmp_le_i32_e32 vcc, v221, v214
	v_add_u32_e32 v221, 11, v219
	s_nop 0
	v_cndmask_b32_e32 v70, v202, v70, vcc
	v_cmp_le_i32_e32 vcc, v221, v214
	v_add_u32_e32 v221, 43, v219
	s_nop 0
	v_cndmask_b32_e32 v87, v202, v87, vcc
	v_cmp_le_i32_e32 vcc, v221, v214
	v_add_u32_e32 v221, 16, v219
	s_nop 0
	v_cndmask_b32_e32 v71, v202, v71, vcc
	v_cmp_le_i32_e32 vcc, v221, v214
	v_add_u32_e32 v221, 48, v219
	s_nop 0
	v_cndmask_b32_e32 v88, v202, v88, vcc
	v_cmp_le_i32_e32 vcc, v221, v214
	v_add_u32_e32 v221, 17, v219
	s_nop 0
	v_cndmask_b32_e32 v72, v202, v72, vcc
	v_cmp_le_i32_e32 vcc, v221, v214
	v_add_u32_e32 v221, 49, v219
	s_nop 0
	v_cndmask_b32_e32 v89, v202, v89, vcc
	v_cmp_le_i32_e32 vcc, v221, v214
	v_add_u32_e32 v221, 18, v219
	s_nop 0
	v_cndmask_b32_e32 v73, v202, v73, vcc
	v_cmp_le_i32_e32 vcc, v221, v214
	v_add_u32_e32 v221, 50, v219
	s_nop 0
	v_cndmask_b32_e32 v90, v202, v90, vcc
	v_cmp_le_i32_e32 vcc, v221, v214
	v_add_u32_e32 v221, 19, v219
	s_nop 0
	v_cndmask_b32_e32 v74, v202, v74, vcc
	v_cmp_le_i32_e32 vcc, v221, v214
	v_add_u32_e32 v221, 51, v219
	s_nop 0
	v_cndmask_b32_e32 v91, v202, v91, vcc
	v_cmp_le_i32_e32 vcc, v221, v214
	v_add_u32_e32 v221, 24, v219
	s_nop 0
	v_cndmask_b32_e32 v75, v202, v75, vcc
	v_cmp_le_i32_e32 vcc, v221, v214
	v_add_u32_e32 v221, 56, v219
	s_nop 0
	v_cndmask_b32_e32 v92, v202, v92, vcc
	v_cmp_le_i32_e32 vcc, v221, v214
	v_add_u32_e32 v221, 25, v219
	s_nop 0
	v_cndmask_b32_e32 v76, v202, v76, vcc
	v_cmp_le_i32_e32 vcc, v221, v214
	v_add_u32_e32 v221, 57, v219
	s_nop 0
	v_cndmask_b32_e32 v93, v202, v93, vcc
	v_cmp_le_i32_e32 vcc, v221, v214
	v_add_u32_e32 v221, 26, v219
	s_nop 0
	v_cndmask_b32_e32 v77, v202, v77, vcc
	v_cmp_le_i32_e32 vcc, v221, v214
	v_add_u32_e32 v221, 58, v219
	s_nop 0
	v_cndmask_b32_e32 v94, v202, v94, vcc
	v_cmp_le_i32_e32 vcc, v221, v214
	v_add_u32_e32 v221, 27, v219
	s_nop 0
	v_cndmask_b32_e32 v78, v202, v78, vcc
	v_cmp_le_i32_e32 vcc, v221, v214
	v_add_u32_e32 v221, 59, v219
	s_nop 0
	v_cndmask_b32_e32 v95, v202, v95, vcc
	v_cmp_le_i32_e32 vcc, v221, v214
	s_nop 1
	v_cndmask_b32_e32 v79, v202, v79, vcc

; #define LAS __attribute__((address_space(3)))
; DI unsigned pk_bf16(float lo, float hi) { unsigned r; asm("v_cvt_pk_bf16_f32 %0, %1, %2" : "=v"(r) : "v"(lo), "v"(hi)); return r; }
; #define MFMA32(a, b, c) __builtin_amdgcn_mfma_f32_32x32x16_bf16((a), (b), (c), 0, 0, 0)
; DI bf16x8 cat4(s16x4 lo, s16x4 hi) { return __builtin_shufflevector(lo, hi, 0, 1, 2, 3, 4, 5, 6, 7); }
; DI void attn_unit(const Params& P, LAS unsigned char* lds, int b, int h, int qb, bool dry) {
;     ...
;         typedef float f32x2_ __attribute__((ext_vector_type(2)));
;         f32x2_ ls2 = {0.f, 0.f};
;         const f32x2_ m2 = {mrun, mrun};
; #pragma unroll
;         for (int i = 0; i < 16; i += 2) {
;             f32x2_ t = (f32x2_){s0[i], s0[i + 1]} - m2; t.x = __builtin_amdgcn_exp2f(t.x); t.y = __builtin_amdgcn_exp2f(t.y); ls2 += t; s0[i] = t.x; s0[i + 1] = t.y;
;             f32x2_ u = (f32x2_){s1[i], s1[i + 1]} - m2; u.x = __builtin_amdgcn_exp2f(u.x); u.y = __builtin_amdgcn_exp2f(u.y); ls2 += u; s1[i] = u.x; s1[i + 1] = u.y;
;         }
;         lrun += ls2.x + ls2.y;
; #pragma unroll
;         for (int s2 = 0; s2 < 2; ++s2) {
;             u32x4 t0, t1;
;             t0.x = pk_bf16(s0[8 * s2 + 0], s0[8 * s2 + 1]); t0.y = pk_bf16(s0[8 * s2 + 2], s0[8 * s2 + 3]); t0.z = pk_bf16(s0[8 * s2 + 4], s0[8 * s2 + 5]); t0.w = pk_bf16(s0[8 * s2 + 6], s0[8 * s2 + 7]);
;             t1.x = pk_bf16(s1[8 * s2 + 0], s1[8 * s2 + 1]); t1.y = pk_bf16(s1[8 * s2 + 2], s1[8 * s2 + 3]); t1.z = pk_bf16(s1[8 * s2 + 4], s1[8 * s2 + 5]); t1.w = pk_bf16(s1[8 * s2 + 6], s1[8 * s2 + 7]);
;             pf[0][s2] = __builtin_bit_cast(bf16x8, t0); pf[1][s2] = __builtin_bit_cast(bf16x8, t1);
;         }
;     };
;     auto pv = [&](int vslot) {
;         const LAS unsigned char* vb_ = Vs + vslot * VS_BYTES + r * VS_STRIDE + 8 * hh;
; #pragma unroll
;         for (int kb = 0; kb < 2; ++kb)
; #pragma unroll
;             for (int s2 = 0; s2 < 2; ++s2)
; #pragma unroll
;                 for (int d = 0; d < 4; ++d) {
;                     const LAS unsigned char* p = vb_ + d * 32 * VS_STRIDE + (32 * kb + 16 * s2) * 2;
;                     const bf16x8 a = cat4(*(const LAS s16x4*)p, *(const LAS s16x4*)(p + 16));
;                     o[d] = MFMA32(a, pf[kb][s2], o[d]);
;                 }
;     };
.LBB0_40:
	v_add_u32_e32 v221, 0xc800, v216
	ds_read2_b64 v[222:225], v221 offset1:2
	v_pk_add_f32 v[86:87], v[86:87], v[194:195] op_sel_hi:[1,0] neg_lo:[0,1] neg_hi:[0,1]
	v_add_u32_e32 v240, 0xf800, v216
	v_exp_f32_e32 v230, v86
	v_exp_f32_e32 v231, v87
	v_pk_add_f32 v[86:87], v[88:89], v[194:195] op_sel_hi:[1,0] neg_lo:[0,1] neg_hi:[0,1]
	v_pk_add_f32 v[90:91], v[90:91], v[194:195] op_sel_hi:[1,0] neg_lo:[0,1] neg_hi:[0,1]
	v_exp_f32_e32 v232, v86
	v_exp_f32_e32 v233, v87
	ds_read2_b64 v[86:89], v240 offset0:96 offset1:98
	v_exp_f32_e32 v234, v90
	v_exp_f32_e32 v235, v91
	v_pk_add_f32 v[90:91], v[92:93], v[194:195] op_sel_hi:[1,0] neg_lo:[0,1] neg_hi:[0,1]
	v_pk_add_f32 v[80:81], v[80:81], v[194:195] op_sel_hi:[1,0] neg_lo:[0,1] neg_hi:[0,1]
	v_pk_add_f32 v[82:83], v[82:83], v[194:195] op_sel_hi:[1,0] neg_lo:[0,1] neg_hi:[0,1]
	v_pk_add_f32 v[84:85], v[84:85], v[194:195] op_sel_hi:[1,0] neg_lo:[0,1] neg_hi:[0,1]
	v_add_u32_e32 v238, 0xd800, v216
	v_exp_f32_e32 v236, v90
	v_exp_f32_e32 v237, v91
	ds_read2_b64 v[90:93], v221 offset0:4 offset1:6
	v_exp_f32_e32 v80, v80
	v_exp_f32_e32 v81, v81
	v_exp_f32_e32 v82, v82
	v_exp_f32_e32 v83, v83
	v_exp_f32_e32 v84, v84
	v_exp_f32_e32 v85, v85
	v_cvt_pk_bf16_f32 v226, v80, v81
	v_cvt_pk_bf16_f32 v227, v82, v83
	v_cvt_pk_bf16_f32 v228, v84, v85
	v_cvt_pk_bf16_f32 v229, v230, v231
	v_add_u32_e32 v239, 0xe800, v216
	s_waitcnt lgkmcnt(0)
	v_mfma_f32_32x32x16_bf16 v[48:63], v[222:225], v[226:229], v[48:63]
	ds_read2_b64 v[222:225], v238 offset0:32 offset1:34
	v_add_f32_e64 v64, v64, -v194
	v_add_f32_e64 v65, v65, -v194
	v_add_f32_e64 v72, v72, -v194
	v_add_f32_e64 v73, v73, -v194
	v_mfma_f32_32x32x16_bf16 v[0:15], v[86:89], v[226:229], v[0:15]
	v_add_f32_e64 v86, v94, -v194
	v_add_f32_e64 v87, v95, -v194
	v_cvt_pk_bf16_f32 v88, v236, v237
	v_exp_f32_e32 v94, v86
	v_exp_f32_e32 v95, v87
	v_cvt_pk_bf16_f32 v86, v232, v233
	v_cvt_pk_bf16_f32 v87, v234, v235
	v_cvt_pk_bf16_f32 v89, v94, v95
	s_waitcnt lgkmcnt(0)
	v_mfma_f32_32x32x16_bf16 v[32:47], v[222:225], v[226:229], v[32:47]
	ds_read2_b64 v[222:225], v239 offset0:64 offset1:66
	v_mfma_f32_32x32x16_bf16 v[48:63], v[90:93], v[86:89], v[48:63]
	ds_read2_b64 v[90:93], v238 offset0:36 offset1:38
	s_waitcnt lgkmcnt(0)
	v_mfma_f32_32x32x16_bf16 v[32:47], v[90:93], v[86:89], v[32:47]
	ds_read2_b64 v[90:93], v239 offset0:68 offset1:70
	v_mfma_f32_32x32x16_bf16 v[16:31], v[222:225], v[226:229], v[16:31]
	v_exp_f32_e32 v226, v64
	v_exp_f32_e32 v227, v65
	v_pk_add_f32 v[64:65], v[66:67], v[194:195] op_sel_hi:[1,0] neg_lo:[0,1] neg_hi:[0,1]
	ds_read2_b64 v[222:225], v240 offset0:100 offset1:102
	s_waitcnt lgkmcnt(0)
	v_mfma_f32_32x32x16_bf16 v[16:31], v[90:93], v[86:89], v[16:31]
	v_exp_f32_e32 v90, v64
	v_exp_f32_e32 v91, v65
	v_pk_add_f32 v[64:65], v[68:69], v[194:195] op_sel_hi:[1,0] neg_lo:[0,1] neg_hi:[0,1]
	v_pk_add_f32 v[68:69], v[70:71], v[194:195] op_sel_hi:[1,0] neg_lo:[0,1] neg_hi:[0,1]
	v_exp_f32_e32 v92, v64
	v_exp_f32_e32 v93, v65
	ds_read2_b64 v[64:67], v221 offset0:8 offset1:10
	v_mfma_f32_32x32x16_bf16 v[0:15], v[222:225], v[86:89], v[0:15]
	v_exp_f32_e32 v222, v68
	v_exp_f32_e32 v223, v69
	v_cvt_pk_bf16_f32 v68, v226, v227
	v_cvt_pk_bf16_f32 v69, v90, v91
	v_cvt_pk_bf16_f32 v70, v92, v93
	v_cvt_pk_bf16_f32 v71, v222, v223
	ds_read2_b64 v[86:89], v240 offset0:104 offset1:106
	s_waitcnt lgkmcnt(0)
	v_mfma_f32_32x32x16_bf16 v[48:63], v[64:67], v[68:71], v[48:63]
	ds_read2_b64 v[64:67], v238 offset0:40 offset1:42
	v_exp_f32_e32 v224, v72
	v_exp_f32_e32 v225, v73
	v_pk_add_f32 v[72:73], v[80:81], 0 op_sel_hi:[1,0]
	s_nop 0
	v_pk_add_f32 v[72:73], v[226:227], v[72:73]
	s_waitcnt lgkmcnt(0)
	v_mfma_f32_32x32x16_bf16 v[32:47], v[64:67], v[68:71], v[32:47]
	ds_read2_b64 v[64:67], v239 offset0:72 offset1:74
	v_add_f32_e64 v72, v82, v72
	v_add_f32_e64 v73, v83, v73
	v_add_f32_e64 v72, v90, v72
	v_add_f32_e64 v73, v91, v73
	v_pk_add_f32 v[80:81], v[84:85], v[72:73]
	s_waitcnt lgkmcnt(0)
	v_mfma_f32_32x32x16_bf16 v[16:31], v[64:67], v[68:71], v[16:31]
	v_add_f32_e64 v64, v74, -v194
	v_add_f32_e64 v65, v75, -v194
	ds_read2_b64 v[72:75], v239 offset0:76 offset1:78
	v_exp_f32_e32 v228, v64
	v_exp_f32_e32 v229, v65
	v_pk_add_f32 v[64:65], v[76:77], v[194:195] op_sel_hi:[1,0] neg_lo:[0,1] neg_hi:[0,1]
	s_nop 0
	v_exp_f32_e32 v76, v64
	v_exp_f32_e32 v77, v65
	ds_read2_b64 v[64:67], v221 offset0:12 offset1:14
	v_mfma_f32_32x32x16_bf16 v[0:15], v[86:89], v[68:71], v[0:15]
	v_add_f32_e64 v68, v78, -v194
	v_add_f32_e64 v69, v79, -v194
	v_cvt_pk_bf16_f32 v70, v76, v77
	v_exp_f32_e32 v78, v68
	v_exp_f32_e32 v79, v69
	v_cvt_pk_bf16_f32 v68, v224, v225
	v_cvt_pk_bf16_f32 v69, v228, v229
	v_cvt_pk_bf16_f32 v71, v78, v79
	s_waitcnt lgkmcnt(0)
	v_mfma_f32_32x32x16_bf16 v[48:63], v[64:67], v[68:71], v[48:63]
	ds_read2_b64 v[64:67], v238 offset0:44 offset1:46
	s_waitcnt lgkmcnt(0)
	v_mfma_f32_32x32x16_bf16 v[32:47], v[64:67], v[68:71], v[32:47]
	v_add_f32_e64 v64, v92, v80
	v_add_f32_e64 v65, v93, v81
	v_add_f32_e64 v64, v230, v64
	v_add_f32_e64 v65, v231, v65
	v_add_f32_e64 v64, v222, v64
	v_add_f32_e64 v65, v223, v65
	v_pk_add_f32 v[64:65], v[232:233], v[64:65]
	v_mfma_f32_32x32x16_bf16 v[16:31], v[72:75], v[68:71], v[16:31]
	v_add_f32_e64 v64, v224, v64
	v_add_f32_e64 v65, v225, v65
	v_add_f32_e64 v80, v234, v64
	v_add_f32_e64 v81, v235, v65
	ds_read2_b64 v[64:67], v240 offset0:108 offset1:110
	v_pk_add_f32 v[72:73], v[228:229], v[80:81]
	s_nop 0
	v_pk_add_f32 v[72:73], v[236:237], v[72:73]
	s_waitcnt lgkmcnt(0)
	v_mfma_f32_32x32x16_bf16 v[0:15], v[64:67], v[68:71], v[0:15]
	v_add_f32_e64 v72, v76, v72
	v_add_f32_e64 v73, v77, v73
	v_add_f32_e64 v72, v94, v72
	v_add_f32_e64 v73, v95, v73
	v_add_f32_e64 v72, v78, v72
	v_add_f32_e64 v73, v79, v73
	v_add_f32_e32 v72, v72, v73
	v_add_f32_e32 v215, v215, v72
	s_branch .Lattn_wdone0

; #define ATT_LOAD(kr, vr, t) do { const bf16_t* kp_ = KVb + (size_t)(t) * 64 * 2048 + kn_off; \
;         kr[0] = *(const u32x4*)kp_; kr[1] = *(const u32x4*)(kp_ + 32 * 2048); kr[2] = *(const u32x4*)(KPEb + (t) * 64 * 64 + kp_off); \
;         const bf16_t* vp_ = VTb + (t) * 64 + v_off; vr[0] = *(const u32x4*)vp_; vr[1] = *(const u32x4*)(vp_ + 64 * SEQ); } while (0)
; #define ATT_TILE(t, slot) do { const int rel_ = (t) - 4 * qb; if (rel_ <= (w >> 1)) { qk_softmax((t), (slot), rel_ == (w >> 1)); pv(slot); } } while (0)
; DI void attn_unit(const Params& P, LAS unsigned char* lds, int b, int h, int qb, bool dry) {
;     ...
;     for (int kt = 0; kt < nt; kt += 2) {
;         const bool more2 = kt + 2 < nt;
;         if (more2) ATT_LOAD(kB, vB, kt + 2);
;         ATT_TILE(kt, 0);
;         ATT_STORE(kA, vA, 1);
;         __syncthreads();
;         if (more2) ATT_LOAD(kA, vA, kt + 3);
;         ATT_TILE(kt + 1, 1);
;         if (more2) ATT_STORE(kB, vB, 0);
;         __syncthreads();
.Lattn_wdone0:
	v_cndmask_b32_e64 v64, 0, 1, s[52:53]
	v_cmp_ne_u32_e64 s[40:41], 1, v64
	s_andn2_b64 vcc, exec, s[52:53]
	s_waitcnt lgkmcnt(0)
	s_barrier
	s_cbranch_vccnz .LBB0_44
	v_add_co_u32_e32 v64, vcc, 0xfffe0000, v192
	s_nop 1
	v_addc_co_u32_e32 v65, vcc, -1, v193, vcc
	global_load_dwordx4 v[144:147], v[64:65], off
	global_load_dwordx4 v[148:151], v[192:193], off
	global_load_dwordx4 v[152:155], v[188:189], off
	v_add_co_u32_e32 v64, vcc, 0xffe00000, v190
	s_nop 1
	v_addc_co_u32_e32 v65, vcc, -1, v191, vcc
	global_load_dwordx4 v[156:159], v[64:65], off
	global_load_dwordx4 v[160:163], v[190:191], off
	s_add_i32 s80, s80, -1
	s_cmp_gt_i32 s80, s26
	s_cbranch_scc0 .LBB0_45

; #define LAS __attribute__((address_space(3)))
; #define MFMA32(a, b, c) __builtin_amdgcn_mfma_f32_32x32x16_bf16((a), (b), (c), 0, 0, 0)
; DI void attn_unit(const Params& P, LAS unsigned char* lds, int b, int h, int qb, bool dry) {
;     ...
;     auto qk_softmax = [&](int kt, int kslot, bool domask) {
;         const LAS unsigned char* kb_ = Ks + kslot * KS_BYTES + r * KS_STRIDE + 16 * hh;
;         f32x16 s0, s1;
;         __builtin_amdgcn_s_setprio(1);
;         { const f32x16 z16 = {0.f, 0.f, 0.f, 0.f, 0.f, 0.f, 0.f, 0.f, 0.f, 0.f, 0.f, 0.f, 0.f, 0.f, 0.f, 0.f};
;           const bf16x8 a0 = *(const LAS bf16x8*)(kb_), a1 = *(const LAS bf16x8*)(kb_ + 32 * KS_STRIDE);
;           s0 = MFMA32(a0, qf[0], z16); s1 = MFMA32(a1, qf[0], z16); }
; #pragma unroll
;         for (int s = 1; s < 12; ++s) {
;             const bf16x8 a0 = *(const LAS bf16x8*)(kb_ + 32 * s), a1 = *(const LAS bf16x8*)(kb_ + 32 * KS_STRIDE + 32 * s);
;             s0 = MFMA32(a0, qf[s], s0); s1 = MFMA32(a1, qf[s], s1);
;         }
;         __builtin_amdgcn_s_setprio(0);
.LBB0_45:
	s_add_i32 s42, s27, s20
	s_cmp_lg_u32 s42, 2
	s_setprio 1
	ds_read_b128 v[222:225], v220 offset:25600
	ds_read_b128 v[226:229], v220 offset:38400
	ds_read_b128 v[230:233], v220 offset:25632
	ds_read_b128 v[234:237], v220 offset:38432
	s_waitcnt lgkmcnt(3)
	v_mfma_f32_32x32x16_bf16 v[80:95], v[222:225], v[96:99], 0
	ds_read_b128 v[222:225], v220 offset:25664
	s_waitcnt lgkmcnt(3)
	v_mfma_f32_32x32x16_bf16 v[64:79], v[226:229], v[96:99], 0
	ds_read_b128 v[226:229], v220 offset:38464
	s_waitcnt lgkmcnt(3)
	v_mfma_f32_32x32x16_bf16 v[80:95], v[230:233], v[100:103], v[80:95]
	ds_read_b128 v[230:233], v220 offset:25696
	s_waitcnt lgkmcnt(3)
	v_mfma_f32_32x32x16_bf16 v[64:79], v[234:237], v[100:103], v[64:79]
	ds_read_b128 v[234:237], v220 offset:38496
	s_waitcnt lgkmcnt(3)
	v_mfma_f32_32x32x16_bf16 v[80:95], v[222:225], v[104:107], v[80:95]
	ds_read_b128 v[222:225], v220 offset:25728
	s_waitcnt lgkmcnt(3)
	v_mfma_f32_32x32x16_bf16 v[64:79], v[226:229], v[104:107], v[64:79]
	ds_read_b128 v[226:229], v220 offset:38528
	s_waitcnt lgkmcnt(3)
	v_mfma_f32_32x32x16_bf16 v[80:95], v[230:233], v[108:111], v[80:95]
	ds_read_b128 v[230:233], v220 offset:25760
	s_waitcnt lgkmcnt(3)
	v_mfma_f32_32x32x16_bf16 v[64:79], v[234:237], v[108:111], v[64:79]
	ds_read_b128 v[234:237], v220 offset:38560
	s_waitcnt lgkmcnt(3)
	v_mfma_f32_32x32x16_bf16 v[80:95], v[222:225], v[112:115], v[80:95]
	ds_read_b128 v[222:225], v220 offset:25792
	s_waitcnt lgkmcnt(3)
	v_mfma_f32_32x32x16_bf16 v[64:79], v[226:229], v[112:115], v[64:79]
	ds_read_b128 v[226:229], v220 offset:38592
	s_waitcnt lgkmcnt(3)
	v_mfma_f32_32x32x16_bf16 v[80:95], v[230:233], v[116:119], v[80:95]
	ds_read_b128 v[230:233], v220 offset:25824
	s_waitcnt lgkmcnt(3)
	v_mfma_f32_32x32x16_bf16 v[64:79], v[234:237], v[116:119], v[64:79]
	ds_read_b128 v[234:237], v220 offset:38624
	s_waitcnt lgkmcnt(3)
	v_mfma_f32_32x32x16_bf16 v[80:95], v[222:225], v[120:123], v[80:95]
	ds_read_b128 v[222:225], v220 offset:25856
	s_waitcnt lgkmcnt(3)
	v_mfma_f32_32x32x16_bf16 v[64:79], v[226:229], v[120:123], v[64:79]
	ds_read_b128 v[226:229], v220 offset:38656
	s_waitcnt lgkmcnt(3)
	v_mfma_f32_32x32x16_bf16 v[80:95], v[230:233], v[124:127], v[80:95]
	ds_read_b128 v[230:233], v220 offset:25888
	s_waitcnt lgkmcnt(3)
	v_mfma_f32_32x32x16_bf16 v[64:79], v[234:237], v[124:127], v[64:79]
	ds_read_b128 v[234:237], v220 offset:38688
	s_waitcnt lgkmcnt(3)
	v_mfma_f32_32x32x16_bf16 v[80:95], v[222:225], v[128:131], v[80:95]
	ds_read_b128 v[222:225], v220 offset:25920
	s_waitcnt lgkmcnt(3)
	v_mfma_f32_32x32x16_bf16 v[64:79], v[226:229], v[128:131], v[64:79]
	ds_read_b128 v[226:229], v220 offset:38720
	s_waitcnt lgkmcnt(3)
	v_mfma_f32_32x32x16_bf16 v[80:95], v[230:233], v[132:135], v[80:95]
	ds_read_b128 v[230:233], v220 offset:25952
	s_waitcnt lgkmcnt(3)
	v_mfma_f32_32x32x16_bf16 v[64:79], v[234:237], v[132:135], v[64:79]
	ds_read_b128 v[234:237], v220 offset:38752
	s_waitcnt lgkmcnt(3)
	v_mfma_f32_32x32x16_bf16 v[80:95], v[222:225], v[136:139], v[80:95]
	s_waitcnt lgkmcnt(2)
	v_mfma_f32_32x32x16_bf16 v[64:79], v[226:229], v[136:139], v[64:79]
	s_waitcnt lgkmcnt(1)
	v_mfma_f32_32x32x16_bf16 v[80:95], v[230:233], v[140:143], v[80:95]
	s_waitcnt lgkmcnt(0)
	v_mfma_f32_32x32x16_bf16 v[64:79], v[234:237], v[140:143], v[64:79]
	s_setprio 0
	s_nop 0
	s_mov_b64 vcc, s[40:41]
	s_cbranch_vccnz .Lattn_hw1_skip
	s_waitcnt vmcnt(5)
	ds_write_b128 v207, v[164:167]
	ds_write_b128 v207, v[168:171] offset:12800
	ds_write_b128 v208, v[172:175] offset:256
	ds_write2_b64 v210, v[176:177], v[178:179] offset1:1
	ds_write2_b64 v211, v[180:181], v[182:183] offset1:1
; DI void attn_unit(const Params& P, LAS unsigned char* lds, int b, int h, int qb, bool dry) {
;     ...
;         if (domask) {
;             const int qg = q0 + r, kbase = 64 * kt + 4 * hh;
; #pragma unroll
;             for (int i = 0; i < 16; ++i) { const int kk = kbase + (i & 3) + 8 * (i >> 2);
;                 if (kk > qg) s0[i] = -INFINITY;
;                 if (kk + 32 > qg) s1[i] = -INFINITY; }
;         }
.Lattn_hw1_skip:
	s_cbranch_scc1 .LBB0_47
	v_add_u32_e32 v221, 0x60, v219
	v_add_u32_e32 v220, 64, v219
	v_cmp_le_i32_e32 vcc, v221, v214
	s_nop 6
	v_cndmask_b32_e32 v64, v202, v64, vcc
	v_cmp_lt_i32_e32 vcc, v220, v214
	s_nop 1
	v_cndmask_b32_e32 v81, v202, v81, vcc
	v_cmp_le_i32_e32 vcc, v220, v214
	v_add_u32_e32 v220, 0x61, v219
	s_nop 0
	v_cndmask_b32_e32 v80, v202, v80, vcc
	v_cmp_le_i32_e32 vcc, v220, v214
	v_add_u32_e32 v220, 0x42, v219
	s_nop 0
	v_cndmask_b32_e32 v65, v202, v65, vcc
	v_cmp_le_i32_e32 vcc, v220, v214
	v_add_u32_e32 v220, 0x62, v219
	s_nop 0
	v_cndmask_b32_e32 v82, v202, v82, vcc
	v_cmp_le_i32_e32 vcc, v220, v214
	v_add_u32_e32 v220, 0x43, v219
	s_nop 0
	v_cndmask_b32_e32 v66, v202, v66, vcc
	v_cmp_le_i32_e32 vcc, v220, v214
	v_add_u32_e32 v220, 0x63, v219
	s_nop 0
	v_cndmask_b32_e32 v83, v202, v83, vcc
	v_cmp_le_i32_e32 vcc, v220, v214
	v_add_u32_e32 v220, 0x48, v219
	s_nop 0
	v_cndmask_b32_e32 v67, v202, v67, vcc
	v_cmp_le_i32_e32 vcc, v220, v214
	v_add_u32_e32 v220, 0x68, v219
	s_nop 0
	v_cndmask_b32_e32 v84, v202, v84, vcc
	v_cmp_le_i32_e32 vcc, v220, v214
	v_add_u32_e32 v220, 0x49, v219
	s_nop 0
	v_cndmask_b32_e32 v68, v202, v68, vcc
	v_cmp_le_i32_e32 vcc, v220, v214
	v_add_u32_e32 v220, 0x69, v219
	s_nop 0
	v_cndmask_b32_e32 v85, v202, v85, vcc
	v_cmp_le_i32_e32 vcc, v220, v214
	v_add_u32_e32 v220, 0x4a, v219
	s_nop 0
	v_cndmask_b32_e32 v69, v202, v69, vcc
	v_cmp_le_i32_e32 vcc, v220, v214
	v_add_u32_e32 v220, 0x6a, v219
	s_nop 0
	v_cndmask_b32_e32 v86, v202, v86, vcc
	v_cmp_le_i32_e32 vcc, v220, v214
	v_add_u32_e32 v220, 0x4b, v219
	s_nop 0
	v_cndmask_b32_e32 v70, v202, v70, vcc
	v_cmp_le_i32_e32 vcc, v220, v214
	v_add_u32_e32 v220, 0x6b, v219
	s_nop 0
	v_cndmask_b32_e32 v87, v202, v87, vcc
	v_cmp_le_i32_e32 vcc, v220, v214
	v_add_u32_e32 v220, 0x50, v219
	s_nop 0
	v_cndmask_b32_e32 v71, v202, v71, vcc
	v_cmp_le_i32_e32 vcc, v220, v214
	v_add_u32_e32 v220, 0x70, v219
	s_nop 0
	v_cndmask_b32_e32 v88, v202, v88, vcc
	v_cmp_le_i32_e32 vcc, v220, v214
	v_add_u32_e32 v220, 0x51, v219
	s_nop 0
	v_cndmask_b32_e32 v72, v202, v72, vcc
	v_cmp_le_i32_e32 vcc, v220, v214
	v_add_u32_e32 v220, 0x71, v219
	s_nop 0
	v_cndmask_b32_e32 v89, v202, v89, vcc
	v_cmp_le_i32_e32 vcc, v220, v214
	v_add_u32_e32 v220, 0x52, v219
	s_nop 0
	v_cndmask_b32_e32 v73, v202, v73, vcc
	v_cmp_le_i32_e32 vcc, v220, v214
	v_add_u32_e32 v220, 0x72, v219
	s_nop 0
	v_cndmask_b32_e32 v90, v202, v90, vcc
	v_cmp_le_i32_e32 vcc, v220, v214
	v_add_u32_e32 v220, 0x53, v219
	s_nop 0
	v_cndmask_b32_e32 v74, v202, v74, vcc
	v_cmp_le_i32_e32 vcc, v220, v214
	v_add_u32_e32 v220, 0x73, v219
	s_nop 0
	v_cndmask_b32_e32 v91, v202, v91, vcc
	v_cmp_le_i32_e32 vcc, v220, v214
	v_add_u32_e32 v220, 0x58, v219
	s_nop 0
	v_cndmask_b32_e32 v75, v202, v75, vcc
	v_cmp_le_i32_e32 vcc, v220, v214
	v_add_u32_e32 v220, 0x78, v219
	s_nop 0
	v_cndmask_b32_e32 v92, v202, v92, vcc
	v_cmp_le_i32_e32 vcc, v220, v214
	v_add_u32_e32 v220, 0x59, v219
	s_nop 0
	v_cndmask_b32_e32 v76, v202, v76, vcc
	v_cmp_le_i32_e32 vcc, v220, v214
	v_add_u32_e32 v220, 0x79, v219
	s_nop 0
	v_cndmask_b32_e32 v93, v202, v93, vcc
	v_cmp_le_i32_e32 vcc, v220, v214
	v_add_u32_e32 v220, 0x5a, v219
	s_nop 0
	v_cndmask_b32_e32 v77, v202, v77, vcc
	v_cmp_le_i32_e32 vcc, v220, v214
	v_add_u32_e32 v220, 0x7a, v219
	s_nop 0
	v_cndmask_b32_e32 v94, v202, v94, vcc
	v_cmp_le_i32_e32 vcc, v220, v214
	v_add_u32_e32 v220, 0x5b, v219
	s_nop 0
	v_cndmask_b32_e32 v78, v202, v78, vcc
	v_cmp_le_i32_e32 vcc, v220, v214
	v_add_u32_e32 v220, 0x7b, v219
	s_nop 0
	v_cndmask_b32_e32 v95, v202, v95, vcc
	v_cmp_le_i32_e32 vcc, v220, v214
	s_nop 1
	v_cndmask_b32_e32 v79, v202, v79, vcc

; #define LAS __attribute__((address_space(3)))
; DI unsigned pk_bf16(float lo, float hi) { unsigned r; asm("v_cvt_pk_bf16_f32 %0, %1, %2" : "=v"(r) : "v"(lo), "v"(hi)); return r; }
; #define MFMA32(a, b, c) __builtin_amdgcn_mfma_f32_32x32x16_bf16((a), (b), (c), 0, 0, 0)
; DI bf16x8 cat4(s16x4 lo, s16x4 hi) { return __builtin_shufflevector(lo, hi, 0, 1, 2, 3, 4, 5, 6, 7); }
; DI void attn_unit(const Params& P, LAS unsigned char* lds, int b, int h, int qb, bool dry) {
;     ...
;         typedef float f32x2_ __attribute__((ext_vector_type(2)));
;         f32x2_ ls2 = {0.f, 0.f};
;         const f32x2_ m2 = {mrun, mrun};
; #pragma unroll
;         for (int i = 0; i < 16; i += 2) {
;             f32x2_ t = (f32x2_){s0[i], s0[i + 1]} - m2; t.x = __builtin_amdgcn_exp2f(t.x); t.y = __builtin_amdgcn_exp2f(t.y); ls2 += t; s0[i] = t.x; s0[i + 1] = t.y;
;             f32x2_ u = (f32x2_){s1[i], s1[i + 1]} - m2; u.x = __builtin_amdgcn_exp2f(u.x); u.y = __builtin_amdgcn_exp2f(u.y); ls2 += u; s1[i] = u.x; s1[i + 1] = u.y;
;         }
;         lrun += ls2.x + ls2.y;
; #pragma unroll
;         for (int s2 = 0; s2 < 2; ++s2) {
;             u32x4 t0, t1;
;             t0.x = pk_bf16(s0[8 * s2 + 0], s0[8 * s2 + 1]); t0.y = pk_bf16(s0[8 * s2 + 2], s0[8 * s2 + 3]); t0.z = pk_bf16(s0[8 * s2 + 4], s0[8 * s2 + 5]); t0.w = pk_bf16(s0[8 * s2 + 6], s0[8 * s2 + 7]);
;             t1.x = pk_bf16(s1[8 * s2 + 0], s1[8 * s2 + 1]); t1.y = pk_bf16(s1[8 * s2 + 2], s1[8 * s2 + 3]); t1.z = pk_bf16(s1[8 * s2 + 4], s1[8 * s2 + 5]); t1.w = pk_bf16(s1[8 * s2 + 6], s1[8 * s2 + 7]);
;             pf[0][s2] = __builtin_bit_cast(bf16x8, t0); pf[1][s2] = __builtin_bit_cast(bf16x8, t1);
;         }
;     };
;     auto pv = [&](int vslot) {
;         const LAS unsigned char* vb_ = Vs + vslot * VS_BYTES + r * VS_STRIDE + 8 * hh;
; #pragma unroll
;         for (int kb = 0; kb < 2; ++kb)
; #pragma unroll
;             for (int s2 = 0; s2 < 2; ++s2)
; #pragma unroll
;                 for (int d = 0; d < 4; ++d) {
;                     const LAS unsigned char* p = vb_ + d * 32 * VS_STRIDE + (32 * kb + 16 * s2) * 2;
;                     const bf16x8 a = cat4(*(const LAS s16x4*)p, *(const LAS s16x4*)(p + 16));
;                     o[d] = MFMA32(a, pf[kb][s2], o[d]);
;                 }
;     };
;     ...
;         ATT_TILE(kt + 1, 1);
;         if (more2) ATT_STORE(kB, vB, 0);
;         __syncthreads();
.LBB0_49:
	ds_read2_b64 v[220:223], v218 offset1:2
	v_pk_add_f32 v[86:87], v[86:87], v[194:195] op_sel_hi:[1,0] neg_lo:[0,1] neg_hi:[0,1]
	v_add_u32_e32 v238, 0x3000, v218
	v_exp_f32_e32 v228, v86
	v_exp_f32_e32 v229, v87
	v_pk_add_f32 v[86:87], v[88:89], v[194:195] op_sel_hi:[1,0] neg_lo:[0,1] neg_hi:[0,1]
	v_pk_add_f32 v[90:91], v[90:91], v[194:195] op_sel_hi:[1,0] neg_lo:[0,1] neg_hi:[0,1]
	v_exp_f32_e32 v230, v86
	v_exp_f32_e32 v231, v87
	ds_read2_b64 v[86:89], v238 offset0:96 offset1:98
	v_exp_f32_e32 v232, v90
	v_exp_f32_e32 v233, v91
	v_pk_add_f32 v[90:91], v[92:93], v[194:195] op_sel_hi:[1,0] neg_lo:[0,1] neg_hi:[0,1]
	v_pk_add_f32 v[80:81], v[80:81], v[194:195] op_sel_hi:[1,0] neg_lo:[0,1] neg_hi:[0,1]
	v_pk_add_f32 v[82:83], v[82:83], v[194:195] op_sel_hi:[1,0] neg_lo:[0,1] neg_hi:[0,1]
	v_pk_add_f32 v[84:85], v[84:85], v[194:195] op_sel_hi:[1,0] neg_lo:[0,1] neg_hi:[0,1]
	v_add_u32_e32 v236, 0x1000, v218
	v_exp_f32_e32 v234, v90
	v_exp_f32_e32 v235, v91
	ds_read2_b64 v[90:93], v218 offset0:4 offset1:6
	v_exp_f32_e32 v80, v80
	v_exp_f32_e32 v81, v81
	v_exp_f32_e32 v82, v82
	v_exp_f32_e32 v83, v83
	v_exp_f32_e32 v84, v84
	v_exp_f32_e32 v85, v85
	v_cvt_pk_bf16_f32 v224, v80, v81
	v_cvt_pk_bf16_f32 v225, v82, v83
	v_cvt_pk_bf16_f32 v226, v84, v85
	v_cvt_pk_bf16_f32 v227, v228, v229
	v_add_u32_e32 v237, 0x2000, v218
	s_waitcnt lgkmcnt(0)
	v_mfma_f32_32x32x16_bf16 v[48:63], v[220:223], v[224:227], v[48:63]
	ds_read2_b64 v[220:223], v236 offset0:32 offset1:34
	v_add_f32_e64 v64, v64, -v194
	v_add_f32_e64 v65, v65, -v194
	v_add_f32_e64 v72, v72, -v194
	v_add_f32_e64 v73, v73, -v194
	v_mfma_f32_32x32x16_bf16 v[0:15], v[86:89], v[224:227], v[0:15]
	v_add_f32_e64 v86, v94, -v194
	v_add_f32_e64 v87, v95, -v194
	v_cvt_pk_bf16_f32 v88, v234, v235
	v_exp_f32_e32 v94, v86
	v_exp_f32_e32 v95, v87
	v_cvt_pk_bf16_f32 v86, v230, v231
	v_cvt_pk_bf16_f32 v87, v232, v233
	v_cvt_pk_bf16_f32 v89, v94, v95
	s_waitcnt lgkmcnt(0)
	v_mfma_f32_32x32x16_bf16 v[32:47], v[220:223], v[224:227], v[32:47]
	ds_read2_b64 v[220:223], v237 offset0:64 offset1:66
	v_mfma_f32_32x32x16_bf16 v[48:63], v[90:93], v[86:89], v[48:63]
	ds_read2_b64 v[90:93], v236 offset0:36 offset1:38
	s_waitcnt lgkmcnt(0)
	v_mfma_f32_32x32x16_bf16 v[32:47], v[90:93], v[86:89], v[32:47]
	ds_read2_b64 v[90:93], v237 offset0:68 offset1:70
	v_mfma_f32_32x32x16_bf16 v[16:31], v[220:223], v[224:227], v[16:31]
	v_exp_f32_e32 v224, v64
	v_exp_f32_e32 v225, v65
	v_pk_add_f32 v[64:65], v[66:67], v[194:195] op_sel_hi:[1,0] neg_lo:[0,1] neg_hi:[0,1]
	ds_read2_b64 v[220:223], v238 offset0:100 offset1:102
	s_waitcnt lgkmcnt(0)
	v_mfma_f32_32x32x16_bf16 v[16:31], v[90:93], v[86:89], v[16:31]
	v_exp_f32_e32 v90, v64
	v_exp_f32_e32 v91, v65
	v_pk_add_f32 v[64:65], v[68:69], v[194:195] op_sel_hi:[1,0] neg_lo:[0,1] neg_hi:[0,1]
	v_pk_add_f32 v[68:69], v[70:71], v[194:195] op_sel_hi:[1,0] neg_lo:[0,1] neg_hi:[0,1]
	v_exp_f32_e32 v92, v64
	v_exp_f32_e32 v93, v65
	ds_read2_b64 v[64:67], v218 offset0:8 offset1:10
	v_mfma_f32_32x32x16_bf16 v[0:15], v[220:223], v[86:89], v[0:15]
	v_exp_f32_e32 v220, v68
	v_exp_f32_e32 v221, v69
	v_cvt_pk_bf16_f32 v68, v224, v225
	v_cvt_pk_bf16_f32 v69, v90, v91
	v_cvt_pk_bf16_f32 v70, v92, v93
	v_cvt_pk_bf16_f32 v71, v220, v221
	ds_read2_b64 v[86:89], v238 offset0:104 offset1:106
	s_waitcnt lgkmcnt(0)
	v_mfma_f32_32x32x16_bf16 v[48:63], v[64:67], v[68:71], v[48:63]
	ds_read2_b64 v[64:67], v236 offset0:40 offset1:42
	v_exp_f32_e32 v222, v72
	v_exp_f32_e32 v223, v73
	v_pk_add_f32 v[72:73], v[80:81], 0 op_sel_hi:[1,0]
	s_nop 0
	v_pk_add_f32 v[72:73], v[224:225], v[72:73]
	s_waitcnt lgkmcnt(0)
	v_mfma_f32_32x32x16_bf16 v[32:47], v[64:67], v[68:71], v[32:47]
	ds_read2_b64 v[64:67], v237 offset0:72 offset1:74
	v_add_f32_e64 v72, v82, v72
	v_add_f32_e64 v73, v83, v73
	v_add_f32_e64 v72, v90, v72
	v_add_f32_e64 v73, v91, v73
	v_pk_add_f32 v[80:81], v[84:85], v[72:73]
	s_waitcnt lgkmcnt(0)
	v_mfma_f32_32x32x16_bf16 v[16:31], v[64:67], v[68:71], v[16:31]
	v_add_f32_e64 v64, v74, -v194
	v_add_f32_e64 v65, v75, -v194
	ds_read2_b64 v[72:75], v237 offset0:76 offset1:78
	v_exp_f32_e32 v226, v64
	v_exp_f32_e32 v227, v65
	v_pk_add_f32 v[64:65], v[76:77], v[194:195] op_sel_hi:[1,0] neg_lo:[0,1] neg_hi:[0,1]
	s_nop 0
	v_exp_f32_e32 v76, v64
	v_exp_f32_e32 v77, v65
	ds_read2_b64 v[64:67], v218 offset0:12 offset1:14
	v_mfma_f32_32x32x16_bf16 v[0:15], v[86:89], v[68:71], v[0:15]
	v_add_f32_e64 v68, v78, -v194
	v_add_f32_e64 v69, v79, -v194
	v_cvt_pk_bf16_f32 v70, v76, v77
	v_exp_f32_e32 v78, v68
	v_exp_f32_e32 v79, v69
	v_cvt_pk_bf16_f32 v68, v222, v223
	v_cvt_pk_bf16_f32 v69, v226, v227
	v_cvt_pk_bf16_f32 v71, v78, v79
	s_waitcnt lgkmcnt(0)
	v_mfma_f32_32x32x16_bf16 v[48:63], v[64:67], v[68:71], v[48:63]
	ds_read2_b64 v[64:67], v236 offset0:44 offset1:46
	s_waitcnt lgkmcnt(0)
	v_mfma_f32_32x32x16_bf16 v[32:47], v[64:67], v[68:71], v[32:47]
	v_add_f32_e64 v64, v92, v80
	v_add_f32_e64 v65, v93, v81
	v_add_f32_e64 v64, v228, v64
	v_add_f32_e64 v65, v229, v65
	v_add_f32_e64 v64, v220, v64
	v_add_f32_e64 v65, v221, v65
	v_pk_add_f32 v[64:65], v[230:231], v[64:65]
	v_mfma_f32_32x32x16_bf16 v[16:31], v[72:75], v[68:71], v[16:31]
	v_add_f32_e64 v64, v222, v64
	v_add_f32_e64 v65, v223, v65
	v_add_f32_e64 v80, v232, v64
	v_add_f32_e64 v81, v233, v65
	ds_read2_b64 v[64:67], v238 offset0:108 offset1:110
	v_pk_add_f32 v[72:73], v[226:227], v[80:81]
	s_nop 0
	v_pk_add_f32 v[72:73], v[234:235], v[72:73]
	s_waitcnt lgkmcnt(0)
	v_mfma_f32_32x32x16_bf16 v[0:15], v[64:67], v[68:71], v[0:15]
	v_add_f32_e64 v72, v76, v72
	v_add_f32_e64 v73, v77, v73
	v_add_f32_e64 v72, v94, v72
	v_add_f32_e64 v73, v95, v73
	v_add_f32_e64 v72, v78, v72
	v_add_f32_e64 v73, v79, v73
	v_add_f32_e32 v72, v72, v73
	v_add_f32_e32 v215, v215, v72
	s_branch .LBB0_32
.LBB0_50:
	s_waitcnt vmcnt(5)
	ds_write_b128 v207, v[164:167]
	ds_write_b128 v207, v[168:171] offset:12800
	ds_write_b128 v208, v[172:175] offset:256
	ds_write2_b64 v210, v[176:177], v[178:179] offset1:1
	ds_write2_b64 v211, v[180:181], v[182:183] offset1:1
	s_branch .LBB0_32

; #define LAS __attribute__((address_space(3)))
; #define MFMA32(a, b, c) __builtin_amdgcn_mfma_f32_32x32x16_bf16((a), (b), (c), 0, 0, 0)
; DI void attn_unit(const Params& P, LAS unsigned char* lds, int b, int h, int qb, bool dry) {
;     ...
;     auto qk_softmax = [&](int kt, int kslot, bool domask) {
;         const LAS unsigned char* kb_ = Ks + kslot * KS_BYTES + r * KS_STRIDE + 16 * hh;
;         f32x16 s0, s1;
;         __builtin_amdgcn_s_setprio(1);
;         { const f32x16 z16 = {0.f, 0.f, 0.f, 0.f, 0.f, 0.f, 0.f, 0.f, 0.f, 0.f, 0.f, 0.f, 0.f, 0.f, 0.f, 0.f};
;           const bf16x8 a0 = *(const LAS bf16x8*)(kb_), a1 = *(const LAS bf16x8*)(kb_ + 32 * KS_STRIDE);
;           s0 = MFMA32(a0, qf[0], z16); s1 = MFMA32(a1, qf[0], z16); }
; #pragma unroll
;         for (int s = 1; s < 12; ++s) {
;             const bf16x8 a0 = *(const LAS bf16x8*)(kb_ + 32 * s), a1 = *(const LAS bf16x8*)(kb_ + 32 * KS_STRIDE + 32 * s);
;             s0 = MFMA32(a0, qf[s], s0); s1 = MFMA32(a1, qf[s], s1);
;         }
;         __builtin_amdgcn_s_setprio(0);
.LBB0_55:
	s_add_i32 s37, s52, s20
	s_add_i32 s40, s37, -2
	s_cmp_gt_i32 s40, s36
	v_add_u32_e32 v220, v213, v184
	s_cbranch_scc1 .LBB0_61
	s_add_i32 s40, s27, s20
	s_cmp_lg_u32 s40, 2
	s_setprio 1
	ds_read_b128 v[222:225], v220
	ds_read_b128 v[226:229], v220 offset:12800
	ds_read_b128 v[230:233], v220 offset:32
	ds_read_b128 v[234:237], v220 offset:12832
	s_waitcnt lgkmcnt(3)
	v_mfma_f32_32x32x16_bf16 v[80:95], v[222:225], v[96:99], 0
	ds_read_b128 v[222:225], v220 offset:64
	s_waitcnt lgkmcnt(3)
	v_mfma_f32_32x32x16_bf16 v[64:79], v[226:229], v[96:99], 0
	ds_read_b128 v[226:229], v220 offset:12864
	s_waitcnt lgkmcnt(3)
	v_mfma_f32_32x32x16_bf16 v[80:95], v[230:233], v[100:103], v[80:95]
	ds_read_b128 v[230:233], v220 offset:96
	s_waitcnt lgkmcnt(3)
	v_mfma_f32_32x32x16_bf16 v[64:79], v[234:237], v[100:103], v[64:79]
	ds_read_b128 v[234:237], v220 offset:12896
	s_waitcnt lgkmcnt(3)
	v_mfma_f32_32x32x16_bf16 v[80:95], v[222:225], v[104:107], v[80:95]
	ds_read_b128 v[222:225], v220 offset:128
	s_waitcnt lgkmcnt(3)
	v_mfma_f32_32x32x16_bf16 v[64:79], v[226:229], v[104:107], v[64:79]
	ds_read_b128 v[226:229], v220 offset:12928
	s_waitcnt lgkmcnt(3)
	v_mfma_f32_32x32x16_bf16 v[80:95], v[230:233], v[108:111], v[80:95]
	ds_read_b128 v[230:233], v220 offset:160
	s_waitcnt lgkmcnt(3)
	v_mfma_f32_32x32x16_bf16 v[64:79], v[234:237], v[108:111], v[64:79]
	ds_read_b128 v[234:237], v220 offset:12960
	s_waitcnt lgkmcnt(3)
	v_mfma_f32_32x32x16_bf16 v[80:95], v[222:225], v[112:115], v[80:95]
	ds_read_b128 v[222:225], v220 offset:192
	s_waitcnt lgkmcnt(3)
	v_mfma_f32_32x32x16_bf16 v[64:79], v[226:229], v[112:115], v[64:79]
	ds_read_b128 v[226:229], v220 offset:12992
	s_waitcnt lgkmcnt(3)
	v_mfma_f32_32x32x16_bf16 v[80:95], v[230:233], v[116:119], v[80:95]
	ds_read_b128 v[230:233], v220 offset:224
	s_waitcnt lgkmcnt(3)
	v_mfma_f32_32x32x16_bf16 v[64:79], v[234:237], v[116:119], v[64:79]
	ds_read_b128 v[234:237], v220 offset:13024
	s_waitcnt lgkmcnt(3)
	v_mfma_f32_32x32x16_bf16 v[80:95], v[222:225], v[120:123], v[80:95]
	ds_read_b128 v[222:225], v220 offset:256
	s_waitcnt lgkmcnt(3)
	v_mfma_f32_32x32x16_bf16 v[64:79], v[226:229], v[120:123], v[64:79]
	ds_read_b128 v[226:229], v220 offset:13056
	s_waitcnt lgkmcnt(3)
	v_mfma_f32_32x32x16_bf16 v[80:95], v[230:233], v[124:127], v[80:95]
	ds_read_b128 v[230:233], v220 offset:288
	s_waitcnt lgkmcnt(3)
	v_mfma_f32_32x32x16_bf16 v[64:79], v[234:237], v[124:127], v[64:79]
	ds_read_b128 v[234:237], v220 offset:13088
	s_waitcnt lgkmcnt(3)
	v_mfma_f32_32x32x16_bf16 v[80:95], v[222:225], v[128:131], v[80:95]
	ds_read_b128 v[222:225], v220 offset:320
	s_waitcnt lgkmcnt(3)
	v_mfma_f32_32x32x16_bf16 v[64:79], v[226:229], v[128:131], v[64:79]
	ds_read_b128 v[226:229], v220 offset:13120
	s_waitcnt lgkmcnt(3)
	v_mfma_f32_32x32x16_bf16 v[80:95], v[230:233], v[132:135], v[80:95]
	ds_read_b128 v[230:233], v220 offset:352
	s_waitcnt lgkmcnt(3)
	v_mfma_f32_32x32x16_bf16 v[64:79], v[234:237], v[132:135], v[64:79]
	ds_read_b128 v[234:237], v220 offset:13152
	s_waitcnt lgkmcnt(3)
	v_mfma_f32_32x32x16_bf16 v[80:95], v[222:225], v[136:139], v[80:95]
	s_waitcnt lgkmcnt(2)
	v_mfma_f32_32x32x16_bf16 v[64:79], v[226:229], v[136:139], v[64:79]
	s_waitcnt lgkmcnt(1)
	v_mfma_f32_32x32x16_bf16 v[80:95], v[230:233], v[140:143], v[80:95]
	s_waitcnt lgkmcnt(0)
	v_mfma_f32_32x32x16_bf16 v[64:79], v[234:237], v[140:143], v[64:79]
	s_setprio 0
	s_nop 0
	s_mov_b64 vcc, s[30:31]
	s_cbranch_vccnz .Lattn_hw2_v5
	s_waitcnt vmcnt(0)
	s_branch .Lattn_hw2_go

; #define ATT_LOAD(kr, vr, t) do { const bf16_t* kp_ = KVb + (size_t)(t) * 64 * 2048 + kn_off; \
;         kr[0] = *(const u32x4*)kp_; kr[1] = *(const u32x4*)(kp_ + 32 * 2048); kr[2] = *(const u32x4*)(KPEb + (t) * 64 * 64 + kp_off); \
;         const bf16_t* vp_ = VTb + (t) * 64 + v_off; vr[0] = *(const u32x4*)vp_; vr[1] = *(const u32x4*)(vp_ + 64 * SEQ); } while (0)
; #define ATT_TILE(t, slot) do { const int rel_ = (t) - 4 * qb; if (rel_ <= (w >> 1)) { qk_softmax((t), (slot), rel_ == (w >> 1)); pv(slot); } } while (0)
; DI void attn_unit(const Params& P, LAS unsigned char* lds, int b, int h, int qb, bool dry) {
;     ...
;     for (int kt = 0; kt < nt; kt += 2) {
;         const bool more2 = kt + 2 < nt;
;         if (more2) ATT_LOAD(kB, vB, kt + 2);
;         ATT_TILE(kt, 0);
;         ATT_STORE(kA, vA, 1);
;         __syncthreads();
;         if (more2) ATT_LOAD(kA, vA, kt + 3);
;         ATT_TILE(kt + 1, 1);
;         if (more2) ATT_STORE(kB, vB, 0);
;         __syncthreads();
.Lattn_wdone2:
	v_cndmask_b32_e64 v64, 0, 1, s[30:31]
	v_cmp_ne_u32_e64 s[40:41], 1, v64
	s_andn2_b64 vcc, exec, s[30:31]
	s_waitcnt lgkmcnt(0)
	s_barrier
	s_cbranch_vccnz .LBB0_64
	v_add_co_u32_e32 v64, vcc, 0xfffe0000, v192
	s_nop 1
	v_addc_co_u32_e32 v65, vcc, -1, v193, vcc
	global_load_dwordx4 v[144:147], v[64:65], off
	global_load_dwordx4 v[148:151], v[192:193], off
	global_load_dwordx4 v[152:155], v[188:189], off
	v_add_co_u32_e32 v64, vcc, 0xffe00000, v190
	s_nop 1
	v_addc_co_u32_e32 v65, vcc, -1, v191, vcc
	global_load_dwordx4 v[156:159], v[64:65], off
	global_load_dwordx4 v[160:163], v[190:191], off
	s_add_i32 s37, s37, -1
	s_cmp_gt_i32 s37, s36
	s_cbranch_scc0 .LBB0_65

; #define LAS __attribute__((address_space(3)))
; #define MFMA32(a, b, c) __builtin_amdgcn_mfma_f32_32x32x16_bf16((a), (b), (c), 0, 0, 0)
; DI void attn_unit(const Params& P, LAS unsigned char* lds, int b, int h, int qb, bool dry) {
;     ...
;     auto qk_softmax = [&](int kt, int kslot, bool domask) {
;         const LAS unsigned char* kb_ = Ks + kslot * KS_BYTES + r * KS_STRIDE + 16 * hh;
;         f32x16 s0, s1;
;         __builtin_amdgcn_s_setprio(1);
;         { const f32x16 z16 = {0.f, 0.f, 0.f, 0.f, 0.f, 0.f, 0.f, 0.f, 0.f, 0.f, 0.f, 0.f, 0.f, 0.f, 0.f, 0.f};
;           const bf16x8 a0 = *(const LAS bf16x8*)(kb_), a1 = *(const LAS bf16x8*)(kb_ + 32 * KS_STRIDE);
;           s0 = MFMA32(a0, qf[0], z16); s1 = MFMA32(a1, qf[0], z16); }
; #pragma unroll
;         for (int s = 1; s < 12; ++s) {
;             const bf16x8 a0 = *(const LAS bf16x8*)(kb_ + 32 * s), a1 = *(const LAS bf16x8*)(kb_ + 32 * KS_STRIDE + 32 * s);
;             s0 = MFMA32(a0, qf[s], s0); s1 = MFMA32(a1, qf[s], s1);
;         }
;         __builtin_amdgcn_s_setprio(0);
.LBB0_65:
	s_add_i32 s30, s26, s20
	s_cmp_lg_u32 s30, 2
	s_setprio 1
	ds_read_b128 v[222:225], v220 offset:25600
	ds_read_b128 v[226:229], v220 offset:38400
	ds_read_b128 v[230:233], v220 offset:25632
	ds_read_b128 v[234:237], v220 offset:38432
	s_waitcnt lgkmcnt(3)
	v_mfma_f32_32x32x16_bf16 v[80:95], v[222:225], v[96:99], 0
	ds_read_b128 v[222:225], v220 offset:25664
	s_waitcnt lgkmcnt(3)
	v_mfma_f32_32x32x16_bf16 v[64:79], v[226:229], v[96:99], 0
	ds_read_b128 v[226:229], v220 offset:38464
	s_waitcnt lgkmcnt(3)
	v_mfma_f32_32x32x16_bf16 v[80:95], v[230:233], v[100:103], v[80:95]
	ds_read_b128 v[230:233], v220 offset:25696
	s_waitcnt lgkmcnt(3)
	v_mfma_f32_32x32x16_bf16 v[64:79], v[234:237], v[100:103], v[64:79]
	ds_read_b128 v[234:237], v220 offset:38496
	s_waitcnt lgkmcnt(3)
	v_mfma_f32_32x32x16_bf16 v[80:95], v[222:225], v[104:107], v[80:95]
	ds_read_b128 v[222:225], v220 offset:25728
	s_waitcnt lgkmcnt(3)
	v_mfma_f32_32x32x16_bf16 v[64:79], v[226:229], v[104:107], v[64:79]
	ds_read_b128 v[226:229], v220 offset:38528
	s_waitcnt lgkmcnt(3)
	v_mfma_f32_32x32x16_bf16 v[80:95], v[230:233], v[108:111], v[80:95]
	ds_read_b128 v[230:233], v220 offset:25760
	s_waitcnt lgkmcnt(3)
	v_mfma_f32_32x32x16_bf16 v[64:79], v[234:237], v[108:111], v[64:79]
	ds_read_b128 v[234:237], v220 offset:38560
	s_waitcnt lgkmcnt(3)
	v_mfma_f32_32x32x16_bf16 v[80:95], v[222:225], v[112:115], v[80:95]
	ds_read_b128 v[222:225], v220 offset:25792
	s_waitcnt lgkmcnt(3)
	v_mfma_f32_32x32x16_bf16 v[64:79], v[226:229], v[112:115], v[64:79]
	ds_read_b128 v[226:229], v220 offset:38592
	s_waitcnt lgkmcnt(3)
	v_mfma_f32_32x32x16_bf16 v[80:95], v[230:233], v[116:119], v[80:95]
	ds_read_b128 v[230:233], v220 offset:25824
	s_waitcnt lgkmcnt(3)
	v_mfma_f32_32x32x16_bf16 v[64:79], v[234:237], v[116:119], v[64:79]
	ds_read_b128 v[234:237], v220 offset:38624
	s_waitcnt lgkmcnt(3)
	v_mfma_f32_32x32x16_bf16 v[80:95], v[222:225], v[120:123], v[80:95]
	ds_read_b128 v[222:225], v220 offset:25856
	s_waitcnt lgkmcnt(3)
	v_mfma_f32_32x32x16_bf16 v[64:79], v[226:229], v[120:123], v[64:79]
	ds_read_b128 v[226:229], v220 offset:38656
	s_waitcnt lgkmcnt(3)
	v_mfma_f32_32x32x16_bf16 v[80:95], v[230:233], v[124:127], v[80:95]
	ds_read_b128 v[230:233], v220 offset:25888
	s_waitcnt lgkmcnt(3)
	v_mfma_f32_32x32x16_bf16 v[64:79], v[234:237], v[124:127], v[64:79]
	ds_read_b128 v[234:237], v220 offset:38688
	s_waitcnt lgkmcnt(3)
	v_mfma_f32_32x32x16_bf16 v[80:95], v[222:225], v[128:131], v[80:95]
	ds_read_b128 v[222:225], v220 offset:25920
	s_waitcnt lgkmcnt(3)
	v_mfma_f32_32x32x16_bf16 v[64:79], v[226:229], v[128:131], v[64:79]
	ds_read_b128 v[226:229], v220 offset:38720
	s_waitcnt lgkmcnt(3)
	v_mfma_f32_32x32x16_bf16 v[80:95], v[230:233], v[132:135], v[80:95]
	ds_read_b128 v[230:233], v220 offset:25952
	s_waitcnt lgkmcnt(3)
	v_mfma_f32_32x32x16_bf16 v[64:79], v[234:237], v[132:135], v[64:79]
	ds_read_b128 v[234:237], v220 offset:38752
	s_waitcnt lgkmcnt(3)
	v_mfma_f32_32x32x16_bf16 v[80:95], v[222:225], v[136:139], v[80:95]
	s_waitcnt lgkmcnt(2)
	v_mfma_f32_32x32x16_bf16 v[64:79], v[226:229], v[136:139], v[64:79]
	s_waitcnt lgkmcnt(1)
	v_mfma_f32_32x32x16_bf16 v[80:95], v[230:233], v[140:143], v[80:95]
	s_waitcnt lgkmcnt(0)
	v_mfma_f32_32x32x16_bf16 v[64:79], v[234:237], v[140:143], v[64:79]
	s_setprio 0
	s_nop 0
	s_mov_b64 vcc, s[40:41]
	s_cbranch_vccnz .Lattn_hw3_skip
	s_waitcnt vmcnt(5)
	ds_write_b128 v207, v[164:167]
	ds_write_b128 v207, v[168:171] offset:12800
	ds_write_b128 v208, v[172:175] offset:256
	ds_write2_b64 v210, v[176:177], v[178:179] offset1:1
	ds_write2_b64 v211, v[180:181], v[182:183] offset1:1
